# retention: second V-tile DMA issued next to the first at the S-phase head (during the first K-fragment LDS latency) instead of between MFMAs 4 and 5
# speedup vs baseline: 1.1332x; 1.1332x over previous
; #define LAS __attribute__((address_space(3)))
; __device__ __forceinline__ void p2_ret(const Frame& F, ArgsP a, int layer) {
;     ...
;                 { const LAS unsigned char* kb = lds + RT_K0 + bf * 32768 + (32 * wc + kap) * 512;
;     ...
;                   bf16x8 ka[2], kd[2], kc[2];
;                   RT_KRD(ka, 0); RT_KRD(kd, 2); __builtin_amdgcn_sched_barrier(0);
;                   RT_KRD(kc, 4); RT_KMM(ka, 0); if (pre) { RT_DMA_K(kt + 1, bf ^ 1, 0); RT_DMA_V(kt + 1, bf ^ 1, 0); } __builtin_amdgcn_sched_barrier(0);
;                   RT_KRD(ka, 6); RT_KMM(kd, 2); __builtin_amdgcn_sched_barrier(0);
;                   RT_KRD(kd, 8); RT_KMM(kc, 4); if (pre) { RT_DMA_K(kt + 1, bf ^ 1, 1); RT_DMA_V(kt + 1, bf ^ 1, 1); } __builtin_amdgcn_sched_barrier(0);
;                   RT_KRD(kc, 10); RT_KMM(ka, 6); __builtin_amdgcn_sched_barrier(0);
;                   RT_KRD(ka, 12); RT_KMM(kd, 8); if (pre) { RT_DMA_K(kt + 1, bf ^ 1, 2); RT_DMA_V(kt + 1, bf ^ 1, 2); } __builtin_amdgcn_sched_barrier(0);
;                   RT_KRD(kd, 14); RT_KMM(kc, 10); __builtin_amdgcn_sched_barrier(0);
;                   RT_KMM(ka, 12); if (pre) { RT_DMA_K(kt + 1, bf ^ 1, 3); RT_DMA_V(kt + 1, bf ^ 1, 3); } __builtin_amdgcn_sched_barrier(0);
;                   RT_KMM(kd, 14); __builtin_amdgcn_sched_barrier(0);
;     ...
;                 }
;                 { const bool diag = kt >= 2 * qi;
;                   unsigned pk[8];
;                   if (!diag) { const float tf = __builtin_amdgcn_exp2f((float)(128 * (qi - (kt >> 1))) * lg2);
; #pragma unroll
;                       for (int i = 0; i < 8; ++i) pk[i] = cvt_pk_bf16(st[2 * i] * tf, st[2 * i + 1] * tf);
;                   } else { const int lim = wr * 32 + l31 + (2 * qi - kt) * 64 - 32 * wc - 8 * hh;
; #pragma unroll
;                       for (int i = 0; i < 8; ++i) { const int r0 = 2 * i, r1 = 2 * i + 1, o0 = 16 * (r0 >> 3) + (r0 & 7), o1 = 16 * (r1 >> 3) + (r1 & 7);
;                           pk[i] = cvt_pk_bf16((o0 <= lim) ? st[r0] : 0.f, (o1 <= lim) ? st[r1] : 0.f); } }
;                   LAS unsigned char* pw = lds + RT_P + ((wr * 2 + wc) * 2) * 1024 + lane * 16;
;                   *(LAS u32x4*)pw = (u32x4){pk[0], pk[1], pk[2], pk[3]}; *(LAS u32x4*)(pw + 1024) = (u32x4){pk[4], pk[5], pk[6], pk[7]}; }
.LBB0_383:
	v_mov_b32_e32 v0, v207
	s_and_b32 s6, s31, 0x8000
	v_lshlrev_b32_e32 v99, 1, v0
	v_lshrrev_b32_e32 v100, 1, v0
	v_and_b32_e32 v98, 19, v0
	v_and_b32_e32 v99, 8, v99
	v_and_b32_e32 v100, 4, v100
	v_or3_b32 v115, v99, v98, v100
	v_ashrrev_i32_e32 v116, 5, v0
	s_add_i32 s4, s6, 0
	v_or_b32_e32 v98, s80, v115
	v_lshl_add_u32 v227, v98, 9, s4
	v_bitop3_b32 v228, v115, v116, 15 bitop3:0x6c
	v_or_b32_e32 v229, 2, v116
	v_bitop3_b32 v229, v115, v229, 15 bitop3:0x6c
	v_lshl_add_u32 v228, v228, 4, v227
	v_lshl_add_u32 v229, v229, 4, v227
	ds_read_b128 v[98:101], v228
	ds_read_b128 v[190:193], v229
	v_or_b32_e32 v230, 4, v116
	v_bitop3_b32 v230, v115, v230, 15 bitop3:0x6c
	v_or_b32_e32 v231, 6, v116
	v_lshl_add_u32 v230, v230, 4, v227
	v_bitop3_b32 v231, v115, v231, 15 bitop3:0x6c
	v_lshl_add_u32 v231, v231, 4, v227
	ds_read_b128 v[194:197], v230
	ds_read_b128 v[198:201], v231
	v_and_b32_e32 v117, 31, v0
	v_or_b32_e32 v250, 8, v116
	s_xor_b32 s4, s6, 0x8000
	v_bitop3_b32 v250, v115, v250, 15 bitop3:0x6c
	v_or_b32_e32 v251, 10, v116
	s_add_i32 s5, s22, s4
	v_lshl_add_u32 v250, v250, 4, v227
	v_bitop3_b32 v251, v115, v251, 15 bitop3:0x6c
	v_lshl_add_u32 v251, v251, 4, v227
	ds_read_b128 v[202:205], v250
	ds_read_b128 v[212:215], v251
	s_add_i32 s7, s25, s30
	s_add_i32 m0, s33, s4
	s_add_i32 s12, s7, 0x80
	s_mov_b32 s46, s42
	s_mov_b32 s47, s43
	buffer_load_dwordx4 v225, s[44:47], s12 offen lds
	s_add_i32 s4, s4, 0x10000
	s_add_i32 m0, s4, s24
	s_add_i32 s12, s7, 0x100080
	buffer_load_dwordx4 v225, s[44:47], s12 offen lds
	s_waitcnt lgkmcnt(5)
	v_mfma_f32_32x32x16_bf16 v[98:113], v[98:101], v[118:121], 0
	s_waitcnt lgkmcnt(4)
	v_mfma_f32_32x32x16_bf16 v[98:113], v[190:193], v[122:125], v[98:113]
	v_or_b32_e32 v252, 12, v116
	v_or_b32_e32 v253, 14, v116
	v_bitop3_b32 v252, v115, v252, 15 bitop3:0x6c
	v_bitop3_b32 v253, v115, v253, 15 bitop3:0x6c
	v_lshl_add_u32 v252, v252, 4, v227
	v_lshl_add_u32 v253, v253, 4, v227
	ds_read_b128 v[190:193], v252
	ds_read_b128 v[216:219], v253
	s_waitcnt lgkmcnt(5)
	v_mfma_f32_32x32x16_bf16 v[98:113], v[194:197], v[126:129], v[98:113]
	s_waitcnt lgkmcnt(4)
	v_mfma_f32_32x32x16_bf16 v[98:113], v[198:201], v[130:133], v[98:113]
	s_add_i32 s12, s27, 0xfffe0000
	ds_read_b128 v[194:197], v228 offset:256
	ds_read_b128 v[198:201], v229 offset:256
	s_waitcnt lgkmcnt(5)
	v_mfma_f32_32x32x16_bf16 v[98:113], v[202:205], v[134:137], v[98:113]
	s_waitcnt lgkmcnt(4)
	v_mfma_f32_32x32x16_bf16 v[98:113], v[212:215], v[138:141], v[98:113]
	ds_read_b128 v[202:205], v230 offset:256
	ds_read_b128 v[212:215], v231 offset:256
	s_waitcnt lgkmcnt(5)
	v_mfma_f32_32x32x16_bf16 v[98:113], v[190:193], v[142:145], v[98:113]
	s_add_i32 s12, s27, 0xffff0000
	s_waitcnt lgkmcnt(4)
	v_mfma_f32_32x32x16_bf16 v[98:113], v[216:219], v[146:149], v[98:113]
	ds_read_b128 v[190:193], v250 offset:256
	ds_read_b128 v[216:219], v251 offset:256
	s_add_i32 m0, s4, s26
	s_add_i32 s12, s7, 0x200080
	buffer_load_dwordx4 v225, s[44:47], s12 offen lds
	s_waitcnt lgkmcnt(5)
	v_mfma_f32_32x32x16_bf16 v[98:113], v[194:197], v[150:153], v[98:113]
	s_waitcnt lgkmcnt(4)
	v_mfma_f32_32x32x16_bf16 v[98:113], v[198:201], v[154:157], v[98:113]
	s_waitcnt lgkmcnt(3)
	v_mfma_f32_32x32x16_bf16 v[98:113], v[202:205], v[158:161], v[98:113]
	ds_read_b128 v[194:197], v252 offset:256
	ds_read_b128 v[198:201], v253 offset:256
	s_waitcnt lgkmcnt(4)
	v_mfma_f32_32x32x16_bf16 v[98:113], v[212:215], v[162:165], v[98:113]
	s_add_i32 s7, s7, 0x300080
	s_add_i32 m0, s4, s28
	s_waitcnt lgkmcnt(3)
	v_mfma_f32_32x32x16_bf16 v[98:113], v[190:193], v[166:169], v[98:113]
	buffer_load_dwordx4 v225, s[44:47], s7 offen lds
	s_waitcnt lgkmcnt(2)
	v_mfma_f32_32x32x16_bf16 v[98:113], v[216:219], v[170:173], v[98:113]
	s_waitcnt lgkmcnt(1)
	v_mfma_f32_32x32x16_bf16 v[98:113], v[194:197], v[174:177], v[98:113]
	s_waitcnt lgkmcnt(0)
	v_mfma_f32_32x32x16_bf16 v[98:113], v[198:201], v[178:181], v[98:113]
	v_lshlrev_b32_e32 v250, 3, v115
	v_and_b32_e32 v250, 0x70, v250
	s_add_i32 s13, s64, s6
	v_lshl_add_u32 v251, v115, 7, s13
	v_lshlrev_b32_e32 v252, 4, v116
	s_lshl_b32 s14, s80, 1
	v_xad_u32 v246, v250, v252, v251
	v_add_u32_e32 v253, 32, v252
	v_xad_u32 v247, v250, v253, v251
	v_xor_b32_e32 v246, s14, v246
	v_xor_b32_e32 v247, s14, v247
	v_xor_b32_e32 v248, 64, v246
	v_xor_b32_e32 v249, 64, v247
	ds_read_b128 v[234:237], v246
	ds_read_b128 v[238:241], v247
	s_cmp_ge_u32 s91, s29
	s_mov_b64 s[4:5], -1
	s_cbranch_scc0 .LBB0_385
	v_lshlrev_b32_e32 v190, 3, v116
	v_sub_u32_e32 v117, v117, v190
	v_add_u32_e32 v117, s97, v117
	v_cmp_lt_i32_e32 vcc, -1, v117
	s_mov_b64 s[4:5], 0
	s_nop 3
	v_cndmask_b32_e32 v190, 0, v98, vcc
	v_cmp_lt_i32_e32 vcc, 0, v117
	s_nop 1
	v_cndmask_b32_e32 v191, 0, v99, vcc
	v_cmp_lt_i32_e32 vcc, 1, v117
	v_cvt_pk_bf16_f32 v190, v190, v191
	s_nop 1
	v_cndmask_b32_e32 v191, 0, v100, vcc
	v_cmp_lt_i32_e32 vcc, 2, v117
	s_nop 1
	v_cndmask_b32_e32 v192, 0, v101, vcc
	v_cmp_lt_i32_e32 vcc, 3, v117
	v_cvt_pk_bf16_f32 v191, v191, v192
	s_nop 1
	v_cndmask_b32_e32 v192, 0, v102, vcc
	v_cmp_lt_i32_e32 vcc, 4, v117
	s_nop 1
	v_cndmask_b32_e32 v193, 0, v103, vcc
	v_cmp_lt_i32_e32 vcc, 5, v117
	v_cvt_pk_bf16_f32 v192, v192, v193
	s_nop 1
	v_cndmask_b32_e32 v193, 0, v104, vcc
	v_cmp_lt_i32_e32 vcc, 6, v117
	s_nop 1
	v_cndmask_b32_e32 v194, 0, v105, vcc
	v_cmp_lt_i32_e32 vcc, 15, v117
	v_cvt_pk_bf16_f32 v193, v193, v194
	s_nop 1
	v_cndmask_b32_e32 v194, 0, v106, vcc
	v_cmp_lt_i32_e32 vcc, 16, v117
	s_nop 1
	v_cndmask_b32_e32 v195, 0, v107, vcc
	v_cmp_lt_i32_e32 vcc, 17, v117
	v_cvt_pk_bf16_f32 v194, v194, v195
	s_nop 1
	v_cndmask_b32_e32 v195, 0, v108, vcc
	v_cmp_lt_i32_e32 vcc, 18, v117
	s_nop 1
	v_cndmask_b32_e32 v196, 0, v109, vcc
	v_cmp_lt_i32_e32 vcc, 19, v117
	v_cvt_pk_bf16_f32 v195, v195, v196
	s_nop 1
	v_cndmask_b32_e32 v196, 0, v110, vcc
	v_cmp_lt_i32_e32 vcc, 20, v117
	s_nop 1
	v_cndmask_b32_e32 v197, 0, v111, vcc
	v_cmp_lt_i32_e32 vcc, 21, v117
	v_cvt_pk_bf16_f32 v196, v196, v197
	s_nop 1
	v_cndmask_b32_e32 v197, 0, v112, vcc
	v_cmp_lt_i32_e32 vcc, 22, v117
	s_nop 1
	v_cndmask_b32_e32 v117, 0, v113, vcc
	v_cvt_pk_bf16_f32 v197, v197, v117
